# GLA pass-1 item: intra-chunk output block stored as whole 256-byte rows through an LDS image instead of 8-byte stores scattered over 32 rows
# baseline (speedup 1.0000x reference)
.LBB0_195:
	s_or_b64 exec, exec, s[0:1]
	v_and_b32_e32 v57, 31, v33
	v_lshrrev_b32_e32 v62, 5, v54
	v_lshrrev_b32_e32 v0, 1, v33
	v_bitop3_b32 v0, v62, v0, 7 bitop3:0x78
	v_lshlrev_b32_e32 v24, 7, v57
	v_lshl_or_b32 v4, v0, 4, v24
	s_waitcnt lgkmcnt(0)
	s_barrier
	ds_read_b128 v[0:3], v4 offset:4096
	ds_read_b128 v[4:7], v4
	v_bfe_u32 v25, v33, 1, 3
	s_waitcnt lgkmcnt(0)
	v_mfma_f32_32x32x16_bf16 v[0:15], v[0:3], v[4:7], 0
	v_bitop3_b32 v16, v62, v25, 2 bitop3:0x36
	v_lshl_or_b32 v20, v16, 4, v24
	ds_read_b128 v[16:19], v20 offset:4096
	ds_read_b128 v[20:23], v20
	v_bitop3_b32 v26, v62, v25, 4 bitop3:0x36
	v_lshl_or_b32 v26, v26, 4, v24
	v_bitop3_b32 v25, v62, v25, 6 bitop3:0x36
	v_lshl_or_b32 v24, v25, 4, v24
	s_waitcnt lgkmcnt(0)
	v_mfma_f32_32x32x16_bf16 v[0:15], v[16:19], v[20:23], v[0:15]
	ds_read_b128 v[16:19], v26 offset:4096
	ds_read_b128 v[20:23], v26
	v_lshlrev_b32_e32 v34, 2, v62
	v_cmp_lt_u32_e32 vcc, v34, v57
	v_or_b32_e32 v63, 2, v34
	v_or_b32_e32 v64, 3, v34
	v_or_b32_e32 v65, 8, v34
	v_or_b32_e32 v66, 9, v34
	s_waitcnt lgkmcnt(0)
	v_mfma_f32_32x32x16_bf16 v[0:15], v[16:19], v[20:23], v[0:15]
	ds_read_b128 v[16:19], v24 offset:4096
	ds_read_b128 v[20:23], v24
	v_or_b32_e32 v67, 10, v34
	v_or_b32_e32 v68, 11, v34
	v_or_b32_e32 v69, 16, v34
	v_or_b32_e32 v70, 17, v34
	v_or_b32_e32 v71, 18, v34
	s_waitcnt lgkmcnt(0)
	v_mfma_f32_32x32x16_bf16 v[0:15], v[16:19], v[20:23], v[0:15]
	v_or_b32_e32 v72, 19, v34
	v_or_b32_e32 v73, 24, v34
	s_movk_i32 s0, 0x50
	v_or_b32_e32 v74, 25, v34
	v_or_b32_e32 v75, 26, v34
	v_or_b32_e32 v76, 27, v34
	v_cndmask_b32_e64 v152, v192, v193, s[40:41]
	s_nop 4
	v_cndmask_b32_e32 v16, 0, v1, vcc
	v_cmp_le_u32_e32 vcc, v34, v57
	v_ashrrev_i32_e32 v51, 31, v50
	s_nop 0
	v_cndmask_b32_e32 v17, 0, v0, vcc
	v_cmp_le_u32_e32 vcc, v63, v57
	v_or_b32_e32 v0, v50, v57
	v_mul_lo_u32 v0, v0, s0
	v_cndmask_b32_e32 v18, 0, v2, vcc
	v_cmp_le_u32_e32 vcc, v64, v57
	v_readlane_b32 s0, v247, 39
	v_readlane_b32 s1, v247, 40
	v_cndmask_b32_e32 v19, 0, v3, vcc
	v_cmp_le_u32_e32 vcc, v65, v57
	s_nop 1
	v_cndmask_b32_e32 v20, 0, v4, vcc
	v_cmp_le_u32_e32 vcc, v66, v57
	v_cvt_pk_bf16_f32 v4, v17, v16
	s_nop 0
	v_cndmask_b32_e32 v21, 0, v5, vcc
	v_cmp_le_u32_e32 vcc, v67, v57
	v_cvt_pk_bf16_f32 v5, v18, v19
	s_nop 0
	v_cndmask_b32_e32 v22, 0, v6, vcc
	v_cmp_le_u32_e32 vcc, v68, v57
	v_cvt_pk_bf16_f32 v6, v20, v21
	s_nop 0
	v_cndmask_b32_e32 v7, 0, v7, vcc
	v_cmp_le_u32_e32 vcc, v69, v57
	v_cvt_pk_bf16_f32 v7, v22, v7
	s_nop 0
	v_cndmask_b32_e32 v35, 0, v8, vcc
	v_cmp_le_u32_e32 vcc, v70, v57
	s_nop 1
	v_cndmask_b32_e32 v36, 0, v9, vcc
	v_cmp_le_u32_e32 vcc, v71, v57
	s_nop 1
	v_cndmask_b32_e32 v37, 0, v10, vcc
	v_cmp_le_u32_e32 vcc, v72, v57
	s_nop 1
	v_cndmask_b32_e32 v38, 0, v11, vcc
	v_cmp_le_u32_e32 vcc, v73, v57
	s_nop 1
	v_cndmask_b32_e32 v39, 0, v12, vcc
	v_lshlrev_b32_e32 v12, 3, v62
	v_or_b32_e32 v40, v0, v12
	v_add_u32_e32 v8, 0x3000, v40
	ds_read2_b64 v[0:3], v8 offset0:128 offset1:130
	ds_read2_b64 v[8:11], v8 offset0:132 offset1:134
	s_waitcnt lgkmcnt(1)
	v_mfma_f32_32x32x16_bf16 v[16:31], v[0:3], v[4:7], 0
	v_cmp_le_u32_e32 vcc, v74, v57
	v_cvt_pk_bf16_f32 v0, v35, v36
	v_cvt_pk_bf16_f32 v1, v37, v38
	v_cndmask_b32_e32 v13, 0, v13, vcc
	v_cmp_le_u32_e32 vcc, v75, v57
	v_cvt_pk_bf16_f32 v2, v39, v13
	v_bitop3_b32 v4, v33, 31, v33 bitop3:0xc
	v_cndmask_b32_e32 v14, 0, v14, vcc
	v_cmp_le_u32_e32 vcc, v76, v57
	v_mov_b32_e32 v13, v153
	s_nop 0
	v_cndmask_b32_e32 v3, 0, v15, vcc
	v_cvt_pk_bf16_f32 v3, v14, v3
	v_lshl_add_u64 v[14:15], s[0:1], 0, v[152:153]
	s_waitcnt lgkmcnt(0)
	v_mfma_f32_32x32x16_bf16 v[16:31], v[8:11], v[0:3], v[16:31]
	v_add_u32_e32 v8, v40, v12
	ds_read_b128 v[0:3], v8 offset:13312
	v_cndmask_b32_e64 v9, v4, v57, s[40:41]
	v_mul_u32_u24_e32 v4, 0x50, v57
	v_lshl_add_u32 v77, v62, 4, v4
	ds_read_b128 v[4:7], v77 offset:8192
	v_or_b32_e32 v9, v9, v32
	v_lshlrev_b32_e32 v152, 10, v9
	s_waitcnt lgkmcnt(0)
	v_mfma_f32_32x32x16_bf16 v[32:47], v[0:3], v[4:7], 0
	v_lshl_add_u64 v[4:5], v[14:15], 0, v[152:153]
	v_lshl_add_u64 v[4:5], v[48:49], 1, v[4:5]
	v_lshl_add_u64 v[4:5], v[50:51], 1, v[4:5]
	ds_read_b128 v[58:61], v8 offset:13344
	ds_read_b128 v[8:11], v77 offset:8224
	v_lshl_add_u64 v[48:49], v[4:5], 0, v[12:13]
	v_cvt_pk_bf16_f32 v4, v16, v17
	v_cvt_pk_bf16_f32 v5, v18, v19
	v_and_b32_e32 v101, 31, v167
	v_lshrrev_b32_e32 v102, 6, v167
	v_lshlrev_b32_e32 v102, 2, v102
	v_and_b32_e32 v103, 15, v101
	v_xor_b32_e32 v102, v102, v103
	v_lshlrev_b32_e32 v102, 4, v102
	v_bfe_u32 v103, v167, 5, 1
	v_lshl_or_b32 v102, v103, 3, v102
	v_lshl_add_u32 v101, v101, 8, v102
	v_add_u32_e32 v101, 0x8000, v101
	v_xor_b32_e32 v102, 16, v101
	v_xor_b32_e32 v103, 32, v101
	v_xor_b32_e32 v104, 48, v101
	ds_write_b64 v101, v[4:5]
	ds_read_b128 v[4:7], v77 offset:10752
	ds_read_b128 v[16:19], v77 offset:10784
	s_waitcnt lgkmcnt(2)
	v_mfma_f32_32x32x16_bf16 v[32:47], v[58:61], v[8:11], v[32:47]
	v_cvt_pk_bf16_f32 v8, v20, v21
	v_cvt_pk_bf16_f32 v9, v22, v23
	ds_write_b64 v102, v[8:9]
	v_cvt_pk_bf16_f32 v20, v24, v25
	v_cvt_pk_bf16_f32 v21, v26, v27
	ds_write_b64 v103, v[20:21]
	v_cvt_pk_bf16_f32 v20, v28, v29
	s_waitcnt lgkmcnt(1)
	v_mfma_f32_32x32x16_bf16 v[0:15], v[0:3], v[4:7], 0
	v_cvt_pk_bf16_f32 v21, v30, v31
	ds_write_b64 v104, v[20:21]
	s_waitcnt lgkmcnt(0)
	s_barrier
	v_readfirstlane_b32 s100, v48
	v_readfirstlane_b32 s101, v49
	v_lshrrev_b32_e32 v100, 6, v167
	v_lshrrev_b32_e32 v98, 4, v167
	v_readfirstlane_b32 vcc_lo, v100
	v_and_b32_e32 v99, 15, v167
	s_lshl_b32 vcc_lo, vcc_lo, 6
	s_sub_u32 s100, s100, vcc_lo
	s_subb_u32 s101, s101, 0
	s_cmp_lg_u64 s[40:41], 0
	s_cselect_b32 vcc_lo, 0, 0x7c00
	s_sub_u32 s100, s100, vcc_lo
	s_subb_u32 s101, s101, 0
	v_xor_b32_e32 v100, v99, v98
	v_lshlrev_b32_e32 v100, 4, v100
	v_lshl_add_u32 v100, v98, 8, v100
	v_add_u32_e32 v100, 0x8000, v100
	ds_read_b128 v[90:93], v100
	ds_read_b128 v[94:97], v100 offset:4096
	v_sub_u32_e32 v100, 31, v98
	v_cndmask_b32_e64 v98, v100, v98, s[40:41]
	v_lshlrev_b32_e32 v99, 4, v99
	v_lshl_add_u32 v98, v98, 10, v99
	v_xor_b32_e32 v99, 0x4000, v98
	s_waitcnt lgkmcnt(1)
	global_store_dwordx4 v98, v[90:93], s[100:101]
	s_waitcnt lgkmcnt(0)
	global_store_dwordx4 v99, v[94:97], s[100:101]
	v_lshlrev_b32_e32 v22, 7, v63
	v_lshlrev_b32_e32 v23, 7, v64
	v_mfma_f32_32x32x16_bf16 v[0:15], v[58:61], v[16:19], v[0:15]
	v_lshlrev_b32_e32 v16, 12, v55
	v_lshlrev_b32_e32 v18, 9, v62
	v_lshlrev_b32_e32 v19, 1, v57
	v_cvt_pk_bf16_f32 v17, v32, s0
	v_or3_b32 v18, v16, v18, v19
	ds_write_b16 v18, v17
	v_cvt_pk_bf16_f32 v17, v33, s0
	s_nop 4
	v_cvt_pk_bf16_f32 v0, v0, s0
	ds_write_b16 v18, v0 offset:64
	v_cvt_pk_bf16_f32 v0, v1, s0
	ds_write_b16 v18, v17 offset:128
	v_cvt_pk_bf16_f32 v17, v34, s0
	v_or3_b32 v22, v16, v22, v19
	ds_write_b16 v18, v0 offset:192
	v_cvt_pk_bf16_f32 v0, v2, s0
	ds_write_b16 v22, v17
	v_cvt_pk_bf16_f32 v17, v35, s0
	v_or3_b32 v23, v16, v23, v19
	v_lshlrev_b32_e32 v24, 7, v65
	ds_write_b16 v22, v0 offset:64
	v_cvt_pk_bf16_f32 v0, v3, s0
	ds_write_b16 v23, v17
	v_cvt_pk_bf16_f32 v17, v36, s0
	v_or3_b32 v24, v16, v24, v19
	v_lshlrev_b32_e32 v25, 7, v66
	ds_write_b16 v23, v0 offset:64
	v_cvt_pk_bf16_f32 v0, v4, s0
	ds_write_b16 v24, v17
	v_cvt_pk_bf16_f32 v17, v37, s0
	v_or3_b32 v25, v16, v25, v19
	v_lshlrev_b32_e32 v26, 7, v67
	ds_write_b16 v24, v0 offset:64
	v_cvt_pk_bf16_f32 v0, v5, s0
	ds_write_b16 v25, v17
	v_cvt_pk_bf16_f32 v17, v38, s0
	v_or3_b32 v26, v16, v26, v19
	v_lshlrev_b32_e32 v27, 7, v68
	ds_write_b16 v25, v0 offset:64
	v_cvt_pk_bf16_f32 v0, v6, s0
	ds_write_b16 v26, v17
	v_cvt_pk_bf16_f32 v17, v39, s0
	v_or3_b32 v27, v16, v27, v19
	v_lshlrev_b32_e32 v28, 7, v69
	ds_write_b16 v26, v0 offset:64
	v_cvt_pk_bf16_f32 v0, v7, s0
	ds_write_b16 v27, v17
	v_cvt_pk_bf16_f32 v17, v40, s0
	v_or3_b32 v28, v16, v28, v19
	v_lshlrev_b32_e32 v29, 7, v70
	ds_write_b16 v27, v0 offset:64
	v_cvt_pk_bf16_f32 v0, v8, s0
	ds_write_b16 v28, v17
	v_cvt_pk_bf16_f32 v17, v41, s0
	v_or3_b32 v29, v16, v29, v19
	v_lshlrev_b32_e32 v30, 7, v71
	ds_write_b16 v28, v0 offset:64
	v_cvt_pk_bf16_f32 v0, v9, s0
	ds_write_b16 v29, v17
	v_cvt_pk_bf16_f32 v17, v42, s0
	v_or3_b32 v30, v16, v30, v19
	v_lshlrev_b32_e32 v31, 7, v72
	ds_write_b16 v29, v0 offset:64
	v_cvt_pk_bf16_f32 v0, v10, s0
	ds_write_b16 v30, v17
	v_cvt_pk_bf16_f32 v17, v43, s0
	v_or3_b32 v31, v16, v31, v19
	v_lshlrev_b32_e32 v32, 7, v73
	ds_write_b16 v30, v0 offset:64
	v_cvt_pk_bf16_f32 v0, v11, s0
	ds_write_b16 v31, v17
	v_cvt_pk_bf16_f32 v17, v44, s0
	v_or3_b32 v32, v16, v32, v19
	v_lshlrev_b32_e32 v33, 7, v74
	ds_write_b16 v31, v0 offset:64
	v_cvt_pk_bf16_f32 v0, v12, s0
	ds_write_b16 v32, v17
	v_cvt_pk_bf16_f32 v17, v45, s0
	v_or3_b32 v33, v16, v33, v19
	v_lshlrev_b32_e32 v34, 7, v75
	ds_write_b16 v32, v0 offset:64
	v_cvt_pk_bf16_f32 v0, v13, s0
	ds_write_b16 v33, v17
	v_cvt_pk_bf16_f32 v17, v46, s0
	v_or3_b32 v34, v16, v34, v19
	ds_write_b16 v33, v0 offset:64
	v_cvt_pk_bf16_f32 v0, v14, s0
	ds_write_b16 v34, v17
	v_cvt_pk_bf16_f32 v17, v47, s0
	v_lshlrev_b32_e32 v35, 7, v76
	ds_write_b16 v34, v0 offset:64
	v_cvt_pk_bf16_f32 v0, v15, s0
	v_readlane_b32 s0, v249, 10
	v_lshlrev_b64 v[20:21], 14, v[52:53]
	v_or3_b32 v19, v16, v35, v19
	v_readlane_b32 s1, v249, 11
	v_lshlrev_b32_e32 v2, 1, v56
	ds_write_b16 v19, v0 offset:64
	v_lshl_add_u64 v[0:1], s[0:1], 0, v[20:21]
	v_lshrrev_b32_e32 v12, 3, v54
	v_and_b32_e32 v152, 0x70, v2
	v_or_b32_e32 v13, v16, v152
	v_lshl_add_u64 v[8:9], v[0:1], 0, v[152:153]
	v_or_b32_e32 v0, v12, v50
	v_lshl_or_b32 v2, v12, 7, v13
	v_ashrrev_i32_e32 v1, 31, v0
	v_lshlrev_b64 v[4:5], 7, v[0:1]
	ds_read_b128 v[0:3], v2
	v_or_b32_e32 v14, 8, v12
	v_lshl_add_u64 v[10:11], v[8:9], 0, v[4:5]
	v_lshl_or_b32 v4, v14, 7, v13
	ds_read_b128 v[4:7], v4
	s_waitcnt lgkmcnt(1)
	global_store_dwordx4 v[10:11], v[0:3], off
	ds_write_b16 v19, v17
	s_nop 0
	v_or_b32_e32 v0, v14, v50
	v_ashrrev_i32_e32 v1, 31, v0
	v_lshlrev_b64 v[0:1], 7, v[0:1]
	v_lshl_add_u64 v[0:1], v[8:9], 0, v[0:1]
	s_waitcnt lgkmcnt(1)
	global_store_dwordx4 v[0:1], v[4:7], off
	v_or_b32_e32 v0, 16, v12
	v_lshl_or_b32 v2, v0, 7, v13
	v_or_b32_e32 v0, v0, v50
	v_ashrrev_i32_e32 v1, 31, v0
	v_lshlrev_b64 v[4:5], 7, v[0:1]
	ds_read_b128 v[0:3], v2
	v_or_b32_e32 v12, 24, v12
	v_lshl_add_u64 v[10:11], v[8:9], 0, v[4:5]
	v_lshl_or_b32 v4, v12, 7, v13
	ds_read_b128 v[4:7], v4
	s_waitcnt lgkmcnt(1)
	global_store_dwordx4 v[10:11], v[0:3], off
	s_nop 1
	v_or_b32_e32 v0, v12, v50
	v_ashrrev_i32_e32 v1, 31, v0
	v_lshlrev_b64 v[0:1], 7, v[0:1]
	v_lshl_add_u64 v[0:1], v[8:9], 0, v[0:1]
	s_waitcnt lgkmcnt(0)
	global_store_dwordx4 v[0:1], v[4:7], off
